# FFN-up tile order: column-tile index rotated by 3 per XCD so the XCDs stream different weight tiles at a time
# speedup vs baseline: 1.0114x; 1.0114x over previous
.LBB0_934:
	s_and_b64 vcc, exec, s[0:1]
	s_cbranch_vccz .LBB0_951
	s_cmpk_gt_i32 s9, 0xaff
	v_readfirstlane_b32 s1, v198
	s_cbranch_scc1 .LBB0_951
	v_lshlrev_b32_e32 v0, 4, v198
	s_waitcnt lgkmcnt(0)
	v_add_u32_e32 v1, 0x2000, v0
	v_ashrrev_i32_e32 v2, 31, v1
	v_lshrrev_b32_e32 v2, 22, v2
	v_add_u32_e32 v2, v1, v2
	v_ashrrev_i32_e32 v8, 10, v2
	v_mul_i32_i24_e32 v2, 0x400, v8
	v_sub_u32_e32 v1, v1, v2
	v_lshrrev_b32_e32 v2, 4, v1
	v_bitop3_b32 v1, v2, v1, 32 bitop3:0x6c
	v_ashrrev_i32_e32 v2, 31, v1
	v_lshrrev_b32_e32 v2, 26, v2
	v_readlane_b32 s0, v255, 32
	v_add_u32_e32 v2, v1, v2
	v_lshlrev_b32_e32 v3, 3, v8
	s_cmp_eq_u32 s0, 1
	v_ashrrev_i32_e32 v9, 6, v2
	v_and_b32_e32 v3, -16, v3
	s_cselect_b32 s0, 0, 0x2000000
	v_add_u32_e32 v3, v9, v3
	s_add_u32 s16, s91, s0
	v_and_b32_e32 v4, 3, v9
	s_mov_b32 s0, 0x1fffe0
	v_lshrrev_b32_e32 v5, 2, v3
	v_lshlrev_b32_e32 v6, 1, v3
	v_and_b32_e32 v2, 0xc0, v2
	v_and_or_b32 v4, v3, s0, v4
	v_and_b32_e32 v5, 4, v5
	v_and_b32_e32 v6, 24, v6
	v_sub_u32_e32 v1, v1, v2
	v_or3_b32 v4, v4, v5, v6
	v_lshlrev_b32_e32 v5, 5, v8
	v_ashrrev_i16_sdwa v1, v252, sext(v1) dst_sel:DWORD dst_unused:UNUSED_PAD src0_sel:DWORD src1_sel:BYTE_0
	v_and_b32_e32 v5, 32, v5
	v_bfe_i32 v10, v1, 0, 16
	v_add_lshl_u32 v1, v5, v10, 1
	v_lshl_add_u32 v154, v4, 11, v1
	v_lshl_add_u32 v156, v3, 11, v1
	v_bfe_i32 v1, v198, 27, 1
	v_lshrrev_b32_e32 v1, 22, v1
	v_add_u32_e32 v1, v0, v1
	v_and_b32_e32 v1, 0xfffffc00, v1
	v_sub_u32_e32 v0, v0, v1
	v_lshrrev_b32_e32 v1, 4, v0
	v_ashrrev_i32_e32 v2, 31, v198
	v_bitop3_b32 v0, v1, v0, 32 bitop3:0x6c
	v_lshrrev_b32_e32 v2, 26, v2
	v_ashrrev_i32_e32 v1, 31, v0
	v_add_u32_e32 v2, v198, v2
	v_lshrrev_b32_e32 v1, 26, v1
	v_ashrrev_i32_e32 v12, 6, v2
	v_add_u32_e32 v1, v0, v1
	v_lshlrev_b32_e32 v2, 3, v12
	v_ashrrev_i32_e32 v11, 6, v1
	v_and_b32_e32 v2, -16, v2
	s_addc_u32 s38, s90, 0
	v_add_u32_e32 v2, v11, v2
	v_and_b32_e32 v3, 3, v11
	s_ashr_i32 s45, s9, 31
	v_and_or_b32 v3, v2, s0, v3
	s_lshr_b32 s0, s45, 29
	s_add_i32 s0, s9, s0
	s_ashr_i32 s8, s1, 6
	s_ashr_i32 s4, s0, 3
	s_and_b32 s0, s0, -8
	s_ashr_i32 s2, s1, 8
	s_lshl_b32 s39, s8, 10
	s_sub_i32 s0, s9, s0
	s_cmp_lt_i32 s0, 0
	s_movk_i32 s5, 0x161
	s_cselect_b32 s5, s5, 0x160
	s_mul_i32 s0, s5, s0
	s_add_i32 s0, s0, s4
	s_mul_hi_i32 s4, s0, 0x2e8ba2e9
	s_lshr_b32 s5, s4, 31
	s_ashr_i32 s4, s4, 5
	s_add_i32 s4, s4, s5
	s_lshl_b32 s5, s4, 3
	s_mulk_i32 s4, 0xb0
	s_sub_i32 s4, s0, s4
	s_bfe_u32 s0, s4, 0x3001c
	s_add_i32 s6, s4, s0
	s_sext_i32_i16 s0, s6
	s_and_b32 s6, s6, 0xfff8
	s_sub_i32 s4, s4, s6
	s_sext_i32_i16 s4, s4
	v_lshrrev_b32_e32 v4, 2, v2
	v_lshlrev_b32_e32 v5, 1, v2
	v_and_b32_e32 v1, 0xc0, v1
	s_lshr_b32 s0, s0, 3
	s_and_b32 s98, s9, 7
	s_mul_i32 s98, s98, 3
	s_add_i32 s0, s0, s98
	s_sub_i32 s98, s0, 22
	s_cmp_gt_u32 s0, 21
	s_cselect_b32 s0, s98, s0
	s_add_i32 s4, s5, s4
	v_and_b32_e32 v4, 4, v4
	v_and_b32_e32 v5, 24, v5
	v_sub_u32_e32 v0, v0, v1
	s_ashr_i32 s5, s4, 31
	s_bfe_i64 s[14:15], s[0:1], 0x100000
	v_or3_b32 v3, v3, v4, v5
	v_lshlrev_b32_e32 v4, 5, v12
	v_ashrrev_i16_sdwa v0, v252, sext(v0) dst_sel:DWORD dst_unused:UNUSED_PAD src0_sel:DWORD src1_sel:BYTE_0
	s_lshl_b64 s[6:7], s[4:5], 19
	s_lshl_b64 s[14:15], s[14:15], 19
	v_and_b32_e32 v4, 32, v4
	v_bfe_i32 v13, v0, 0, 16
	s_add_u32 s66, s16, s14
	v_add_lshl_u32 v0, v4, v13, 1
	s_addc_u32 s67, s38, s15
	s_add_i32 s47, s39, 0
	v_lshl_add_u32 v96, v3, 11, v0
	s_add_i32 m0, s47, 0x10000
	v_lshl_add_u32 v158, v2, 11, v0
	global_load_lds_dwordx4 v96, s[66:67]
	s_add_i32 m0, s47, 0x12000
	s_add_u32 s14, s66, 0x40000
	global_load_lds_dwordx4 v154, s[66:67]
	s_addc_u32 s15, s67, 0
	s_add_i32 m0, s47, 0x14000
	v_mov_b32_e32 v155, v97
	global_load_lds_dwordx4 v96, s[14:15]
	s_add_i32 m0, s47, 0x16000
	s_add_u32 s42, s52, s6
	s_addc_u32 s43, s53, s7
	s_add_i32 s70, s47, 0x2000
	global_load_lds_dwordx4 v154, s[14:15]
	s_mov_b32 m0, s47
	s_add_u32 s6, s42, 0x40000
	global_load_lds_dwordx4 v158, s[42:43]
	s_mov_b32 m0, s70
	s_addc_u32 s7, s43, 0
	s_add_i32 s71, s47, 0x4000
	global_load_lds_dwordx4 v156, s[42:43]
	s_mov_b32 m0, s71
	s_add_i32 s72, s47, 0x6000
	global_load_lds_dwordx4 v158, s[6:7]
	s_mov_b32 m0, s72
	v_mov_b32_e32 v159, v97
	global_load_lds_dwordx4 v156, s[6:7]
	v_mov_b32_e32 v157, v97
	s_cmp_eq_u32 s2, 1
	v_lshl_add_u64 v[6:7], s[66:67], 0, v[96:97]
	v_lshl_add_u64 v[4:5], s[66:67], 0, v[154:155]
	v_lshl_add_u64 v[0:1], s[42:43], 0, v[158:159]
	s_cselect_b64 s[6:7], -1, 0
	s_cmp_lg_u32 s2, 1
	v_lshl_add_u64 v[2:3], s[42:43], 0, v[156:157]
	s_cbranch_scc1 .LBB0_938
	s_barrier

.LBB0_941:
	s_add_i32 s76, s76, 1
	s_mul_i32 s0, s76, s75
	s_mul_hi_u32 s1, s76, s34
	s_add_i32 s1, s1, s0
	s_mul_i32 s0, s76, s34
	s_add_u32 s24, s0, s9
	s_addc_u32 s25, s1, s45
	v_mov_b64_e32 v[0:1], 0xb00
	v_cmp_lt_i64_e64 s[0:1], s[24:25], v[0:1]
	v_mov_b64_e32 v[0:1], 0xaff
	v_cmp_gt_i64_e32 vcc, s[24:25], v[0:1]
	s_cbranch_vccnz .LBB0_943
	s_ashr_i32 s2, s24, 31
	s_lshr_b32 s2, s2, 29
	s_add_i32 s2, s24, s2
	s_ashr_i32 s8, s2, 3
	s_and_b32 s2, s2, -8
	s_sub_i32 s2, s24, s2
	s_cmp_lt_i32 s2, 0
	s_movk_i32 s14, 0x161
	s_cselect_b32 s14, s14, 0x160
	s_mul_i32 s2, s14, s2
	s_add_i32 s2, s2, s8
	s_mul_hi_i32 s8, s2, 0x2e8ba2e9
	s_lshr_b32 s14, s8, 31
	s_ashr_i32 s8, s8, 5
	s_add_i32 s8, s8, s14
	s_lshl_b32 s14, s8, 3
	s_sub_i32 s15, 0x80, s14
	s_min_i32 s15, s15, 8
	s_abs_i32 s18, s15
	v_cvt_f32_u32_e32 v0, s18
	s_sub_i32 s20, 0, s18
	s_mulk_i32 s8, 0xb0
	s_sub_i32 s2, s2, s8
	v_rcp_iflag_f32_e32 v0, v0
	s_abs_i32 s8, s2
	s_xor_b32 s19, s2, s15
	s_ashr_i32 s19, s19, 31
	v_mul_f32_e32 v0, 0x4f7ffffe, v0
	v_cvt_u32_f32_e32 v0, v0
	s_nop 0
	v_readfirstlane_b32 s21, v0
	s_mul_i32 s20, s20, s21
	s_mul_hi_u32 s20, s21, s20
	s_add_i32 s21, s21, s20
	s_mul_hi_u32 s20, s8, s21
	s_mul_i32 s21, s20, s18
	s_sub_i32 s8, s8, s21
	s_add_i32 s24, s20, 1
	s_sub_i32 s21, s8, s18
	s_cmp_ge_u32 s8, s18
	s_cselect_b32 s20, s24, s20
	s_cselect_b32 s8, s21, s8
	s_add_i32 s21, s20, 1
	s_cmp_ge_u32 s8, s18
	s_cselect_b32 s8, s21, s20
	s_xor_b32 s8, s8, s19
	s_sub_i32 s56, s8, s19
	s_mul_i32 s8, s56, s15
	s_sub_i32 s2, s2, s8
	s_add_i32 s60, s2, s14
	s_and_b32 s98, s9, 7
	s_mul_i32 s98, s98, 3
	s_add_i32 s56, s56, s98
	s_sub_i32 s98, s56, 22
	s_cmp_gt_u32 s56, 21
	s_cselect_b32 s56, s98, s56
